# RG-LRU gate fused into the unit output section: second-half tiles of each direction read the other direction's h and the gate rows and write A2 directly; separate gate loop removed, half the YF/YB tra
# speedup vs baseline: 1.0019x; 1.0019x over previous
.LBB0_270:
	s_waitcnt lgkmcnt(0)
	s_barrier
	ds_read_b128 v[40:43], v117
	ds_read_b128 v[36:39], v117 offset:64
	ds_read_b128 v[44:47], v118 offset:9216
	ds_read_b128 v[48:51], v118 offset:18432
	ds_read_b128 v[52:55], v118 offset:9280
	s_waitcnt lgkmcnt(2)
	v_mfma_f32_16x16x32_bf16 v[44:47], v[40:43], v[44:47], 0
	ds_read_u16 v3, v119
	s_waitcnt lgkmcnt(0)
	v_lshlrev_b32_e32 v3, 16, v3
	v_mfma_f32_16x16x32_bf16 v[44:47], v[36:39], v[52:55], v[44:47]
	ds_read_b128 v[52:55], v118 offset:18496
	v_mfma_f32_16x16x32_bf16 v[48:51], v[40:43], v[48:51], 0
	s_waitcnt lgkmcnt(0)
	v_mfma_f32_16x16x32_bf16 v[48:51], v[36:39], v[52:55], v[48:51]
	s_nop 3
	v_add_f32_e32 v1, v97, v44
	v_mul_f32_e32 v1, 0xbfb8aa3b, v1
	v_exp_f32_e32 v1, v1
	s_nop 0
	v_add_f32_e32 v1, 1.0, v1
	v_rcp_f32_e32 v1, v1
	v_add_f32_e32 v2, v98, v48
	v_mul_f32_e32 v2, 0xbfb8aa3b, v2
	v_exp_f32_e32 v2, v2
	v_mul_f32_e32 v1, v105, v1
	v_mul_f32_e32 v1, 0x3fb8aa3b, v1
	v_exp_f32_e32 v1, v1
	v_add_f32_e32 v2, 1.0, v2
	v_rcp_f32_e32 v2, v2
	v_fma_f32 v44, -v1, v1, 1.0
	v_max_f32_e32 v44, 0, v44
	v_sqrt_f32_e32 v44, v44
	v_mul_f32_e32 v2, v2, v3
	v_mul_f32_e32 v2, v2, v44
	ds_write_b32 v109, v1 offset:27648
	ds_write_b32 v109, v2 offset:44288
	v_add_f32_e32 v1, v97, v45
	v_mul_f32_e32 v1, 0xbfb8aa3b, v1
	v_exp_f32_e32 v1, v1
	v_add_f32_e32 v2, v98, v49
	v_mul_f32_e32 v2, 0xbfb8aa3b, v2
	v_exp_f32_e32 v2, v2
	v_add_f32_e32 v1, 1.0, v1
	v_rcp_f32_e32 v1, v1
	ds_read_u16 v3, v120
	v_add_f32_e32 v2, 1.0, v2
	v_rcp_f32_e32 v2, v2
	v_mul_f32_e32 v1, v105, v1
	v_mul_f32_e32 v1, 0x3fb8aa3b, v1
	v_exp_f32_e32 v1, v1
	s_waitcnt lgkmcnt(0)
	v_lshlrev_b32_e32 v3, 16, v3
	v_mul_f32_e32 v2, v2, v3
	ds_read_u16 v3, v121
	v_fma_f32 v44, -v1, v1, 1.0
	v_max_f32_e32 v44, 0, v44
	v_sqrt_f32_e32 v44, v44
	s_waitcnt lgkmcnt(0)
	v_lshlrev_b32_e32 v3, 16, v3
	v_mul_f32_e32 v2, v2, v44
	ds_write2st64_b32 v110, v1, v2 offset0:108 offset1:173
	v_add_f32_e32 v1, v97, v46
	v_mul_f32_e32 v1, 0xbfb8aa3b, v1
	v_exp_f32_e32 v1, v1
	v_add_f32_e32 v2, v98, v50
	v_mul_f32_e32 v2, 0xbfb8aa3b, v2
	v_exp_f32_e32 v2, v2
	v_add_f32_e32 v1, 1.0, v1
	v_rcp_f32_e32 v1, v1
	v_add_f32_e32 v2, 1.0, v2
	v_rcp_f32_e32 v2, v2
	v_mul_f32_e32 v1, v105, v1
	v_mul_f32_e32 v1, 0x3fb8aa3b, v1
	v_exp_f32_e32 v1, v1
	v_mul_f32_e32 v2, v2, v3
	v_fma_f32 v44, -v1, v1, 1.0
	v_max_f32_e32 v44, 0, v44
	v_sqrt_f32_e32 v44, v44
	s_nop 0
	v_mul_f32_e32 v2, v2, v44
	ds_write_b32 v111, v1 offset:27648
	ds_write_b32 v111, v2 offset:44288
	v_add_f32_e32 v1, v97, v47
	v_mul_f32_e32 v1, 0xbfb8aa3b, v1
	v_exp_f32_e32 v1, v1
	v_add_f32_e32 v2, v98, v51
	v_mul_f32_e32 v2, 0xbfb8aa3b, v2
	v_exp_f32_e32 v2, v2
	v_add_f32_e32 v1, 1.0, v1
	v_rcp_f32_e32 v1, v1
	ds_read_u16 v3, v122
	v_add_f32_e32 v2, 1.0, v2
	v_rcp_f32_e32 v2, v2
	v_mul_f32_e32 v1, v105, v1
	v_mul_f32_e32 v1, 0x3fb8aa3b, v1
	v_exp_f32_e32 v1, v1
	s_waitcnt lgkmcnt(0)
	v_lshlrev_b32_e32 v3, 16, v3
	v_mul_f32_e32 v2, v2, v3
	ds_read_u16 v3, v124
	v_fma_f32 v44, -v1, v1, 1.0
	v_max_f32_e32 v44, 0, v44
	v_sqrt_f32_e32 v44, v44
	s_waitcnt lgkmcnt(0)
	v_lshlrev_b32_e32 v3, 16, v3
	v_mul_f32_e32 v2, v44, v2
	ds_write2st64_b32 v112, v1, v2 offset0:108 offset1:173
	ds_read_b128 v[48:51], v123 offset:18432
	ds_read_b128 v[44:47], v123 offset:9216
	s_waitcnt lgkmcnt(1)
	v_mfma_f32_16x16x32_bf16 v[52:55], v[40:43], v[48:51], 0
	ds_read_b128 v[48:51], v123 offset:9280
	s_waitcnt lgkmcnt(1)
	v_mfma_f32_16x16x32_bf16 v[44:47], v[40:43], v[44:47], 0
	s_waitcnt lgkmcnt(0)
	v_mfma_f32_16x16x32_bf16 v[48:51], v[36:39], v[48:51], v[44:47]
	s_nop 5
	ds_read_b128 v[44:47], v123 offset:18496
	s_nop 0
	v_add_f32_e32 v1, v99, v48
	v_mul_f32_e32 v1, 0xbfb8aa3b, v1
	v_exp_f32_e32 v1, v1
	s_waitcnt lgkmcnt(0)
	v_mfma_f32_16x16x32_bf16 v[44:47], v[36:39], v[44:47], v[52:55]
	v_add_f32_e32 v1, 1.0, v1
	v_rcp_f32_e32 v1, v1
	s_nop 0
	v_mul_f32_e32 v1, v106, v1
	s_nop 3
	v_add_f32_e32 v2, v100, v44
	v_mul_f32_e32 v2, 0xbfb8aa3b, v2
	v_mul_f32_e32 v1, 0x3fb8aa3b, v1
	v_exp_f32_e32 v2, v2
	v_exp_f32_e32 v1, v1
	v_add_f32_e32 v2, 1.0, v2
	v_fma_f32 v44, -v1, v1, 1.0
	v_rcp_f32_e32 v2, v2
	v_max_f32_e32 v44, 0, v44
	v_sqrt_f32_e32 v44, v44
	v_mul_f32_e32 v2, v2, v3
	v_mul_f32_e32 v2, v2, v44
	ds_write_b32 v109, v1 offset:27712
	ds_write_b32 v109, v2 offset:44352
	v_add_f32_e32 v1, v99, v49
	v_mul_f32_e32 v1, 0xbfb8aa3b, v1
	v_exp_f32_e32 v1, v1
	v_add_f32_e32 v2, v100, v45
	v_mul_f32_e32 v2, 0xbfb8aa3b, v2
	v_exp_f32_e32 v2, v2
	v_add_f32_e32 v1, 1.0, v1
	v_rcp_f32_e32 v1, v1
	ds_read_u16 v3, v125
	v_add_f32_e32 v2, 1.0, v2
	v_rcp_f32_e32 v2, v2
	v_mul_f32_e32 v1, v106, v1
	v_mul_f32_e32 v1, 0x3fb8aa3b, v1
	v_exp_f32_e32 v1, v1
	s_waitcnt lgkmcnt(0)
	v_lshlrev_b32_e32 v3, 16, v3
	v_mul_f32_e32 v2, v2, v3
	v_fma_f32 v44, -v1, v1, 1.0
	v_max_f32_e32 v44, 0, v44
	v_sqrt_f32_e32 v44, v44
	s_nop 0
	v_mul_f32_e32 v2, v2, v44
	ds_write_b32 v113, v1 offset:27712
	ds_write_b32 v113, v2 offset:44352
	v_add_f32_e32 v1, v99, v50
	v_mul_f32_e32 v1, 0xbfb8aa3b, v1
	v_exp_f32_e32 v1, v1
	v_add_f32_e32 v2, v100, v46
	v_mul_f32_e32 v2, 0xbfb8aa3b, v2
	v_exp_f32_e32 v2, v2
	v_add_f32_e32 v1, 1.0, v1
	v_rcp_f32_e32 v1, v1
	ds_read_u16 v3, v126
	v_add_f32_e32 v2, 1.0, v2
	v_rcp_f32_e32 v2, v2
	v_mul_f32_e32 v1, v106, v1
	v_mul_f32_e32 v1, 0x3fb8aa3b, v1
	v_exp_f32_e32 v1, v1
	s_waitcnt lgkmcnt(0)
	v_lshlrev_b32_e32 v3, 16, v3
	v_mul_f32_e32 v2, v2, v3
	v_fma_f32 v44, -v1, v1, 1.0
	v_max_f32_e32 v44, 0, v44
	v_sqrt_f32_e32 v44, v44
	s_nop 0
	v_mul_f32_e32 v2, v2, v44
	ds_write_b32 v111, v1 offset:27712
	ds_write_b32 v111, v2 offset:44352
	v_add_f32_e32 v1, v99, v51
	v_mul_f32_e32 v1, 0xbfb8aa3b, v1
	v_exp_f32_e32 v1, v1
	ds_read_u16 v3, v127
	v_add_f32_e32 v1, 1.0, v1
	v_rcp_f32_e32 v2, v1
	v_add_f32_e32 v1, v100, v47
	v_mul_f32_e32 v1, 0xbfb8aa3b, v1
	v_exp_f32_e32 v1, v1
	v_mul_f32_e32 v2, v106, v2
	v_mul_f32_e32 v2, 0x3fb8aa3b, v2
	v_exp_f32_e32 v2, v2
	v_add_f32_e32 v1, 1.0, v1
	v_rcp_f32_e32 v1, v1
	s_waitcnt lgkmcnt(0)
	v_lshlrev_b32_e32 v3, 16, v3
	v_fma_f32 v44, -v2, v2, 1.0
	v_max_f32_e32 v44, 0, v44
	v_sqrt_f32_e32 v44, v44
	v_mul_f32_e32 v1, v1, v3
	v_mul_f32_e32 v1, v44, v1
	ds_write_b32 v114, v2 offset:27712
	ds_write_b32 v114, v1 offset:44352
	ds_read_b128 v[44:47], v128 offset:9216
	ds_read_b128 v[52:55], v128 offset:9280
	s_waitcnt lgkmcnt(1)
	v_mfma_f32_16x16x32_bf16 v[44:47], v[40:43], v[44:47], 0
	ds_read_b128 v[48:51], v128 offset:18432
	ds_read_u16 v3, v129
	s_waitcnt lgkmcnt(0)
	v_lshlrev_b32_e32 v3, 16, v3
	v_mfma_f32_16x16x32_bf16 v[44:47], v[36:39], v[52:55], v[44:47]
	ds_read_b128 v[52:55], v128 offset:18496
	v_mfma_f32_16x16x32_bf16 v[48:51], v[40:43], v[48:51], 0
	s_waitcnt lgkmcnt(0)
	v_mfma_f32_16x16x32_bf16 v[48:51], v[36:39], v[52:55], v[48:51]
	s_nop 3
	v_add_f32_e32 v1, v101, v44
	v_mul_f32_e32 v1, 0xbfb8aa3b, v1
	v_exp_f32_e32 v1, v1
	s_nop 0
	v_add_f32_e32 v1, 1.0, v1
	v_rcp_f32_e32 v1, v1
	v_add_f32_e32 v2, v102, v48
	v_mul_f32_e32 v2, 0xbfb8aa3b, v2
	v_exp_f32_e32 v2, v2
	v_mul_f32_e32 v1, v107, v1
	v_mul_f32_e32 v1, 0x3fb8aa3b, v1
	v_exp_f32_e32 v1, v1
	v_add_f32_e32 v2, 1.0, v2
	v_rcp_f32_e32 v2, v2
	v_fma_f32 v44, -v1, v1, 1.0
	v_max_f32_e32 v44, 0, v44
	v_sqrt_f32_e32 v44, v44
	v_mul_f32_e32 v2, v2, v3
	v_mul_f32_e32 v2, v2, v44
	ds_write_b32 v109, v1 offset:27776
	ds_write_b32 v109, v2 offset:44416
	v_add_f32_e32 v1, v101, v45
	v_mul_f32_e32 v1, 0xbfb8aa3b, v1
	v_exp_f32_e32 v1, v1
	v_add_f32_e32 v2, v102, v49
	v_mul_f32_e32 v2, 0xbfb8aa3b, v2
	v_exp_f32_e32 v2, v2
	v_add_f32_e32 v1, 1.0, v1
	v_rcp_f32_e32 v1, v1
	ds_read_u16 v3, v130
	v_add_f32_e32 v2, 1.0, v2
	v_rcp_f32_e32 v2, v2
	v_mul_f32_e32 v1, v107, v1
	v_mul_f32_e32 v1, 0x3fb8aa3b, v1
	v_exp_f32_e32 v1, v1
	s_waitcnt lgkmcnt(0)
	v_lshlrev_b32_e32 v3, 16, v3
	v_mul_f32_e32 v2, v2, v3
	v_fma_f32 v44, -v1, v1, 1.0
	v_max_f32_e32 v44, 0, v44
	v_sqrt_f32_e32 v44, v44
	s_nop 0
	v_mul_f32_e32 v2, v2, v44
	ds_write_b32 v113, v1 offset:27776
	ds_write_b32 v113, v2 offset:44416
	v_add_f32_e32 v1, v101, v46
	v_mul_f32_e32 v1, 0xbfb8aa3b, v1
	v_exp_f32_e32 v1, v1
	v_add_f32_e32 v2, v102, v50
	v_mul_f32_e32 v2, 0xbfb8aa3b, v2
	v_exp_f32_e32 v2, v2
	v_add_f32_e32 v1, 1.0, v1
	v_rcp_f32_e32 v1, v1
	ds_read_u16 v3, v131
	v_add_f32_e32 v2, 1.0, v2
	v_rcp_f32_e32 v2, v2
	v_mul_f32_e32 v1, v107, v1
	v_mul_f32_e32 v1, 0x3fb8aa3b, v1
	v_exp_f32_e32 v1, v1
	s_waitcnt lgkmcnt(0)
	v_lshlrev_b32_e32 v3, 16, v3
	v_mul_f32_e32 v2, v2, v3
	v_fma_f32 v44, -v1, v1, 1.0
	v_max_f32_e32 v44, 0, v44
	v_sqrt_f32_e32 v44, v44
	s_nop 0
	v_mul_f32_e32 v2, v2, v44
	ds_write_b32 v111, v1 offset:27776
	ds_write_b32 v111, v2 offset:44416
	v_add_f32_e32 v1, v101, v47
	v_mul_f32_e32 v1, 0xbfb8aa3b, v1
	v_exp_f32_e32 v1, v1
	v_add_f32_e32 v2, v102, v51
	v_mul_f32_e32 v2, 0xbfb8aa3b, v2
	v_exp_f32_e32 v2, v2
	v_add_f32_e32 v1, 1.0, v1
	v_rcp_f32_e32 v1, v1
	ds_read_u16 v3, v132
	v_add_f32_e32 v2, 1.0, v2
	v_rcp_f32_e32 v2, v2
	v_mul_f32_e32 v1, v107, v1
	v_mul_f32_e32 v1, 0x3fb8aa3b, v1
	v_exp_f32_e32 v1, v1
	s_waitcnt lgkmcnt(0)
	v_lshlrev_b32_e32 v3, 16, v3
	v_mul_f32_e32 v2, v2, v3
	v_fma_f32 v44, -v1, v1, 1.0
	v_max_f32_e32 v44, 0, v44
	v_sqrt_f32_e32 v44, v44
	s_nop 0
	v_mul_f32_e32 v2, v44, v2
	ds_write_b32 v114, v1 offset:27776
	ds_write_b32 v114, v2 offset:44416
	ds_read_b128 v[44:47], v133 offset:9216
	ds_read_b128 v[48:51], v133 offset:18432
	s_waitcnt lgkmcnt(1)
	v_mfma_f32_16x16x32_bf16 v[44:47], v[40:43], v[44:47], 0
	ds_read_u16 v3, v134
	s_waitcnt lgkmcnt(0)
	v_lshlrev_b32_e32 v3, 16, v3
	v_mfma_f32_16x16x32_bf16 v[48:51], v[40:43], v[48:51], 0
	ds_read_b128 v[40:43], v133 offset:9280
	s_waitcnt lgkmcnt(0)
	v_mfma_f32_16x16x32_bf16 v[40:43], v[36:39], v[40:43], v[44:47]
	s_nop 2
	ds_read_b128 v[44:47], v133 offset:18496
	s_waitcnt lgkmcnt(0)
	v_mfma_f32_16x16x32_bf16 v[36:39], v[36:39], v[44:47], v[48:51]
	s_nop 1
	v_add_f32_e32 v1, v103, v40
	v_mul_f32_e32 v1, 0xbfb8aa3b, v1
	v_exp_f32_e32 v1, v1
	s_nop 2
	v_add_f32_e32 v2, v104, v36
	v_mul_f32_e32 v2, 0xbfb8aa3b, v2
	v_exp_f32_e32 v2, v2
	v_add_f32_e32 v1, 1.0, v1
	v_rcp_f32_e32 v1, v1
	v_add_f32_e32 v2, 1.0, v2
	v_rcp_f32_e32 v2, v2
	v_mul_f32_e32 v1, v108, v1
	v_mul_f32_e32 v1, 0x3fb8aa3b, v1
	v_exp_f32_e32 v1, v1
	v_mul_f32_e32 v2, v2, v3
	v_fma_f32 v36, -v1, v1, 1.0
	v_max_f32_e32 v36, 0, v36
	v_sqrt_f32_e32 v36, v36
	s_nop 0
	v_mul_f32_e32 v2, v2, v36
	ds_write_b32 v109, v1 offset:27840
	ds_write_b32 v109, v2 offset:44480
	v_add_f32_e32 v1, v103, v41
	v_mul_f32_e32 v1, 0xbfb8aa3b, v1
	v_exp_f32_e32 v1, v1
	v_add_f32_e32 v2, v104, v37
	v_mul_f32_e32 v2, 0xbfb8aa3b, v2
	v_exp_f32_e32 v2, v2
	v_add_f32_e32 v1, 1.0, v1
	v_rcp_f32_e32 v1, v1
	ds_read_u16 v3, v135
	v_add_f32_e32 v2, 1.0, v2
	v_rcp_f32_e32 v2, v2
	v_mul_f32_e32 v1, v108, v1
	v_mul_f32_e32 v1, 0x3fb8aa3b, v1
	v_exp_f32_e32 v1, v1
	s_waitcnt lgkmcnt(0)
	v_lshlrev_b32_e32 v3, 16, v3
	v_mul_f32_e32 v2, v2, v3
	v_fma_f32 v36, -v1, v1, 1.0
	v_max_f32_e32 v36, 0, v36
	v_sqrt_f32_e32 v36, v36
	s_nop 0
	v_mul_f32_e32 v2, v2, v36
	ds_write_b32 v113, v1 offset:27840
	ds_write_b32 v113, v2 offset:44480
	v_add_f32_e32 v1, v103, v42
	v_mul_f32_e32 v1, 0xbfb8aa3b, v1
	v_exp_f32_e32 v1, v1
	v_add_f32_e32 v2, v104, v38
	v_mul_f32_e32 v2, 0xbfb8aa3b, v2
	v_exp_f32_e32 v2, v2
	v_add_f32_e32 v1, 1.0, v1
	v_rcp_f32_e32 v1, v1
	ds_read_u16 v3, v136
	v_add_f32_e32 v2, 1.0, v2
	v_rcp_f32_e32 v2, v2
	v_mul_f32_e32 v1, v108, v1
	v_mul_f32_e32 v1, 0x3fb8aa3b, v1
	v_exp_f32_e32 v1, v1
	s_waitcnt lgkmcnt(0)
	v_lshlrev_b32_e32 v3, 16, v3
	v_mul_f32_e32 v2, v2, v3
	v_fma_f32 v36, -v1, v1, 1.0
	v_max_f32_e32 v36, 0, v36
	v_sqrt_f32_e32 v36, v36
	s_nop 0
	v_mul_f32_e32 v2, v2, v36
	ds_write_b32 v111, v1 offset:27840
	ds_write_b32 v111, v2 offset:44480
	v_add_f32_e32 v1, v103, v43
	v_mul_f32_e32 v1, 0xbfb8aa3b, v1
	v_exp_f32_e32 v1, v1
	ds_read_u16 v3, v137
	v_add_f32_e32 v1, 1.0, v1
	v_rcp_f32_e32 v2, v1
	v_add_f32_e32 v1, v104, v39
	v_mul_f32_e32 v1, 0xbfb8aa3b, v1
	v_exp_f32_e32 v1, v1
	v_mul_f32_e32 v2, v108, v2
	v_mul_f32_e32 v2, 0x3fb8aa3b, v2
	v_exp_f32_e32 v2, v2
	v_add_f32_e32 v1, 1.0, v1
	v_rcp_f32_e32 v1, v1
	s_waitcnt lgkmcnt(0)
	v_lshlrev_b32_e32 v3, 16, v3
	v_fma_f32 v36, -v2, v2, 1.0
	v_max_f32_e32 v36, 0, v36
	v_sqrt_f32_e32 v36, v36
	v_mul_f32_e32 v1, v1, v3
	v_mul_f32_e32 v1, v36, v1
	ds_write_b32 v114, v2 offset:27840
	ds_write_b32 v114, v1 offset:44480
	s_waitcnt vmcnt(0) lgkmcnt(0)
	s_barrier
	s_cmp_lt_u32 s34, 2
	s_cbranch_scc1 .Lfg_nold_p
	s_sub_i32 s38, 3, s34
	s_and_b64 s[28:29], s[16:17], exec
	s_cselect_b32 s38, s34, s38
	s_mov_b32 s39, 0xfe000000
	s_cselect_b32 s39, 0x2000000, s39
	s_mov_b32 s41, 0x2000000
	s_cselect_b32 s41, 0x4000000, s41
	s_lshl_b32 s38, s38, 6
	s_add_i32 s38, s38, s50
	v_or_b32_e32 v202, s38, v93
	v_lshl_add_u32 v228, v202, 11, s39
	v_ashrrev_i32_e32 v229, 31, v228
	v_lshl_add_u64 v[228:229], v[78:79], 0, v[228:229]
	v_lshl_add_u32 v238, v202, 12, s41
	v_mov_b32_e32 v239, 0
	v_lshl_add_u64 v[238:239], v[78:79], 0, v[238:239]
	global_load_dwordx4 v[228:231], v[228:229], off
	global_load_dwordx4 v[238:241], v[238:239], off
	v_or_b32_e32 v202, s38, v95
	v_lshl_add_u32 v250, v202, 11, s39
	v_ashrrev_i32_e32 v251, 31, v250
	v_lshl_add_u64 v[250:251], v[78:79], 0, v[250:251]
	v_lshl_add_u32 v202, v202, 12, s41
	v_mov_b32_e32 v203, 0
	v_lshl_add_u64 v[202:203], v[78:79], 0, v[202:203]
	global_load_dwordx4 v[250:253], v[250:251], off
	global_load_dword v69, v[202:203], off
	global_load_dword v90, v[202:203], off offset:4
	global_load_dword v189, v[202:203], off offset:8
	global_load_dword v207, v[202:203], off offset:12
.Lfg_nold_p:
	s_and_b64 s[28:29], s[16:17], exec
	s_cselect_b32 s35, 0, 0x3ffc
	s_cselect_b32 s19, 1, -1
	s_mulk_i32 s19, 0x104
	v_readfirstlane_b32 s32, v92
	s_lshr_b32 s32, s32, 6
	s_and_b32 s32, s32, 3
	v_and_b32_e32 v147, 63, v92
	v_lshl_add_u32 v176, v147, 3, s56
	v_lshl_add_u32 v147, v147, 2, s56
	s_mul_i32 s23, s19, s32
	s_lshl_b32 s23, s23, 4
	s_add_i32 s23, s23, s35
	v_add_u32_e32 v1, s23, v147
	v_add_u32_e32 v2, s19, v1
	v_add_u32_e32 v3, s19, v2
	v_add_u32_e32 v36, s19, v3
	v_add_u32_e32 v37, s19, v36
	v_add_u32_e32 v38, s19, v37
	v_add_u32_e32 v39, s19, v38
	v_add_u32_e32 v40, s19, v39
	v_add_u32_e32 v41, s19, v40
	v_add_u32_e32 v42, s19, v41
	v_add_u32_e32 v43, s19, v42
	v_add_u32_e32 v64, s19, v43
	v_add_u32_e32 v65, s19, v64
	v_add_u32_e32 v66, s19, v65
	v_add_u32_e32 v67, s19, v66
	v_add_u32_e32 v68, s19, v67
	ds_read2st64_b32 v[148:149], v1 offset0:108 offset1:173
	ds_read2st64_b32 v[150:151], v2 offset0:108 offset1:173
	ds_read2st64_b32 v[152:153], v3 offset0:108 offset1:173
	ds_read2st64_b32 v[154:155], v36 offset0:108 offset1:173
	ds_read2st64_b32 v[156:157], v37 offset0:108 offset1:173
	ds_read2st64_b32 v[158:159], v38 offset0:108 offset1:173
	ds_read2st64_b32 v[160:161], v39 offset0:108 offset1:173
	ds_read2st64_b32 v[162:163], v40 offset0:108 offset1:173
	ds_read2st64_b32 v[164:165], v41 offset0:108 offset1:173
	ds_read2st64_b32 v[166:167], v42 offset0:108 offset1:173
	ds_read2st64_b32 v[168:169], v43 offset0:108 offset1:173
	ds_read2st64_b32 v[170:171], v64 offset0:108 offset1:173
	ds_read2st64_b32 v[242:243], v65 offset0:108 offset1:173
	ds_read2st64_b32 v[244:245], v66 offset0:108 offset1:173
	ds_read2st64_b32 v[246:247], v67 offset0:108 offset1:173
	ds_read2st64_b32 v[248:249], v68 offset0:108 offset1:173
	s_lshl_b32 s18, s32, 9
	v_add_u32_e32 v139, s18, v176
	s_waitcnt lgkmcnt(14)
	v_fmac_f32_e32 v151, v150, v149
	v_mul_f32_e32 v150, v150, v148
	s_waitcnt lgkmcnt(13)
	v_fmac_f32_e32 v153, v152, v151
	v_mul_f32_e32 v152, v152, v150
	s_waitcnt lgkmcnt(12)
	v_fmac_f32_e32 v155, v154, v153
	v_mul_f32_e32 v154, v154, v152
	s_waitcnt lgkmcnt(11)
	v_fmac_f32_e32 v157, v156, v155
	v_mul_f32_e32 v156, v156, v154
	s_waitcnt lgkmcnt(10)
	v_fmac_f32_e32 v159, v158, v157
	v_mul_f32_e32 v158, v158, v156
	s_waitcnt lgkmcnt(9)
	v_fmac_f32_e32 v161, v160, v159
	v_mul_f32_e32 v160, v160, v158
	s_waitcnt lgkmcnt(8)
	v_fmac_f32_e32 v163, v162, v161
	v_mul_f32_e32 v162, v162, v160
	s_waitcnt lgkmcnt(7)
	v_fmac_f32_e32 v165, v164, v163
	v_mul_f32_e32 v164, v164, v162
	s_waitcnt lgkmcnt(6)
	v_fmac_f32_e32 v167, v166, v165
	v_mul_f32_e32 v166, v166, v164
	s_waitcnt lgkmcnt(5)
	v_fmac_f32_e32 v169, v168, v167
	v_mul_f32_e32 v168, v168, v166
	s_waitcnt lgkmcnt(4)
	v_fmac_f32_e32 v171, v170, v169
	v_mul_f32_e32 v170, v170, v168
	s_waitcnt lgkmcnt(3)
	v_fmac_f32_e32 v243, v242, v171
	v_mul_f32_e32 v242, v242, v170
	s_waitcnt lgkmcnt(2)
	v_fmac_f32_e32 v245, v244, v243
	v_mul_f32_e32 v244, v244, v242
	s_waitcnt lgkmcnt(1)
	v_fmac_f32_e32 v247, v246, v245
	v_mul_f32_e32 v246, v246, v244
	s_waitcnt lgkmcnt(0)
	v_fmac_f32_e32 v249, v248, v247
	v_mul_f32_e32 v248, v248, v246
	ds_write_b64 v139, v[248:249] offset:61440
	s_cmp_lg_u32 s34, 0
	s_cbranch_scc1 .Lps_skipcw_p
	s_cmp_lg_u32 s32, 0
	s_cbranch_scc1 .Lps_skipcw_p
	ds_write_b32 v147, v91 offset:63488

.LBB0_273:
	s_or_b64 exec, exec, s[20:21]
	s_waitcnt lgkmcnt(0)
	s_barrier
	s_sub_i32 s20, 3, s34
	s_and_b64 s[18:19], s[16:17], exec
	s_cselect_b32 s18, s34, s20
	s_lshl_b32 s18, s18, 6
	s_add_i32 s18, s18, s50
	s_and_b64 s[98:99], s[16:17], exec
	s_mov_b32 s61, 0xd000000
	s_cselect_b32 s61, 0xf000000, s61
	s_cmp_lt_u32 s34, 2
	s_cbranch_scc0 .Lfg_out_p
	v_add_u32_e32 v1, 0xad00, v138
	ds_read2_b32 v[2:3], v1 offset1:1
	v_add_u32_e32 v1, 0xad08, v138
	ds_read2_b32 v[38:39], v1 offset1:1
	v_add_u32_e32 v1, 0xad10, v138
	ds_read2_b32 v[40:41], v1 offset1:1
	v_add_u32_e32 v1, 0xad18, v138
	ds_read2_b32 v[42:43], v1 offset1:1
	s_waitcnt lgkmcnt(3)
	v_cvt_pk_bf16_f32 v36, v2, v3
	v_or_b32_e32 v2, s18, v93
	v_mov_b32_e32 v3, v0
	v_lshlrev_b64 v[2:3], 11, v[2:3]
	s_waitcnt lgkmcnt(2)
	v_cvt_pk_bf16_f32 v37, v38, v39
	s_waitcnt lgkmcnt(1)
	v_cvt_pk_bf16_f32 v38, v40, v41
	s_waitcnt lgkmcnt(0)
	v_cvt_pk_bf16_f32 v39, v42, v43
	v_lshl_add_u64 v[2:3], v[78:79], 0, v[2:3]
	global_store_dwordx4 v[2:3], v[36:39], off
	v_add_u32_e32 v1, 0xcd80, v138
	ds_read2_b32 v[2:3], v1 offset1:1
	v_add_u32_e32 v1, 0xcd88, v138
	ds_read2_b32 v[38:39], v1 offset1:1
	v_add_u32_e32 v1, 0xcd90, v138
	ds_read2_b32 v[40:41], v1 offset1:1
	v_add_u32_e32 v1, 0xcd98, v138
	ds_read2_b32 v[42:43], v1 offset1:1
	s_waitcnt lgkmcnt(3)
	v_cvt_pk_bf16_f32 v36, v2, v3
	v_or_b32_e32 v2, s18, v95
	v_mov_b32_e32 v3, v0
	v_lshlrev_b64 v[2:3], 11, v[2:3]
	s_waitcnt lgkmcnt(2)
	v_cvt_pk_bf16_f32 v37, v38, v39
	s_waitcnt lgkmcnt(1)
	v_cvt_pk_bf16_f32 v38, v40, v41
	s_waitcnt lgkmcnt(0)
	v_cvt_pk_bf16_f32 v39, v42, v43
	v_lshl_add_u64 v[2:3], v[78:79], 0, v[2:3]
	global_store_dwordx4 v[2:3], v[36:39], off
	s_branch .Lfg_join_p
.Lfg_out_p:
	v_add_u32_e32 v1, 0xad00, v138
	ds_read2_b32 v[148:149], v1 offset1:1
	v_add_u32_e32 v1, 0xad08, v138
	ds_read2_b32 v[150:151], v1 offset1:1
	v_add_u32_e32 v1, 0xad10, v138
	ds_read2_b32 v[152:153], v1 offset1:1
	v_add_u32_e32 v1, 0xad18, v138
	ds_read2_b32 v[154:155], v1 offset1:1
	v_or_b32_e32 v2, s18, v93
	v_lshl_add_u32 v2, v2, 11, s61
	v_mov_b32_e32 v3, 0
	v_lshl_add_u64 v[2:3], v[78:79], 0, v[2:3]
	s_waitcnt vmcnt(0) lgkmcnt(0)
	v_lshlrev_b32_e32 v156, 16, v238
	v_and_b32_e32 v157, 0xffff0000, v238
	v_lshlrev_b32_e32 v158, 16, v228
	v_and_b32_e32 v159, 0xffff0000, v228
	v_add_f32_e32 v158, v158, v148
	v_add_f32_e32 v159, v159, v149
	v_mul_f32_e32 v160, 0x3d372713, v156
	v_mul_f32_e32 v161, 0x3d372713, v157
	v_mul_f32_e32 v160, v160, v156
	v_mul_f32_e32 v161, v161, v157
	v_fma_f32 v160, v160, v156, v156
	v_fma_f32 v161, v161, v157, v157
	v_mul_f32_e32 v160, 0x3f4c422a, v160
	v_mul_f32_e32 v161, 0x3f4c422a, v161
	v_mul_f32_e32 v160, -2.0, v160
	v_mul_f32_e32 v161, -2.0, v161
	v_mul_f32_e32 v160, 0x3fb8aa3b, v160
	v_mul_f32_e32 v161, 0x3fb8aa3b, v161
	v_exp_f32_e32 v160, v160
	v_exp_f32_e32 v161, v161
	v_add_f32_e32 v160, 1.0, v160
	v_add_f32_e32 v161, 1.0, v161
	v_rcp_f32_e32 v160, v160
	v_rcp_f32_e32 v161, v161
	v_mul_f32_e32 v160, v156, v160
	v_mul_f32_e32 v161, v157, v161
	v_mul_f32_e32 v158, v158, v160
	v_mul_f32_e32 v159, v159, v161
	v_cvt_pk_bf16_f32 v36, v158, v159
	v_lshlrev_b32_e32 v156, 16, v239
	v_and_b32_e32 v157, 0xffff0000, v239
	v_lshlrev_b32_e32 v158, 16, v229
	v_and_b32_e32 v159, 0xffff0000, v229
	v_add_f32_e32 v158, v158, v150
	v_add_f32_e32 v159, v159, v151
	v_mul_f32_e32 v160, 0x3d372713, v156
	v_mul_f32_e32 v161, 0x3d372713, v157
	v_mul_f32_e32 v160, v160, v156
	v_mul_f32_e32 v161, v161, v157
	v_fma_f32 v160, v160, v156, v156
	v_fma_f32 v161, v161, v157, v157
	v_mul_f32_e32 v160, 0x3f4c422a, v160
	v_mul_f32_e32 v161, 0x3f4c422a, v161
	v_mul_f32_e32 v160, -2.0, v160
	v_mul_f32_e32 v161, -2.0, v161
	v_mul_f32_e32 v160, 0x3fb8aa3b, v160
	v_mul_f32_e32 v161, 0x3fb8aa3b, v161
	v_exp_f32_e32 v160, v160
	v_exp_f32_e32 v161, v161
	v_add_f32_e32 v160, 1.0, v160
	v_add_f32_e32 v161, 1.0, v161
	v_rcp_f32_e32 v160, v160
	v_rcp_f32_e32 v161, v161
	v_mul_f32_e32 v160, v156, v160
	v_mul_f32_e32 v161, v157, v161
	v_mul_f32_e32 v158, v158, v160
	v_mul_f32_e32 v159, v159, v161
	v_cvt_pk_bf16_f32 v37, v158, v159
	v_lshlrev_b32_e32 v156, 16, v240
	v_and_b32_e32 v157, 0xffff0000, v240
	v_lshlrev_b32_e32 v158, 16, v230
	v_and_b32_e32 v159, 0xffff0000, v230
	v_add_f32_e32 v158, v158, v152
	v_add_f32_e32 v159, v159, v153
	v_mul_f32_e32 v160, 0x3d372713, v156
	v_mul_f32_e32 v161, 0x3d372713, v157
	v_mul_f32_e32 v160, v160, v156
	v_mul_f32_e32 v161, v161, v157
	v_fma_f32 v160, v160, v156, v156
	v_fma_f32 v161, v161, v157, v157
	v_mul_f32_e32 v160, 0x3f4c422a, v160
	v_mul_f32_e32 v161, 0x3f4c422a, v161
	v_mul_f32_e32 v160, -2.0, v160
	v_mul_f32_e32 v161, -2.0, v161
	v_mul_f32_e32 v160, 0x3fb8aa3b, v160
	v_mul_f32_e32 v161, 0x3fb8aa3b, v161
	v_exp_f32_e32 v160, v160
	v_exp_f32_e32 v161, v161
	v_add_f32_e32 v160, 1.0, v160
	v_add_f32_e32 v161, 1.0, v161
	v_rcp_f32_e32 v160, v160
	v_rcp_f32_e32 v161, v161
	v_mul_f32_e32 v160, v156, v160
	v_mul_f32_e32 v161, v157, v161
	v_mul_f32_e32 v158, v158, v160
	v_mul_f32_e32 v159, v159, v161
	v_cvt_pk_bf16_f32 v38, v158, v159
	v_lshlrev_b32_e32 v156, 16, v241
	v_and_b32_e32 v157, 0xffff0000, v241
	v_lshlrev_b32_e32 v158, 16, v231
	v_and_b32_e32 v159, 0xffff0000, v231
	v_add_f32_e32 v158, v158, v154
	v_add_f32_e32 v159, v159, v155
	v_mul_f32_e32 v160, 0x3d372713, v156
	v_mul_f32_e32 v161, 0x3d372713, v157
	v_mul_f32_e32 v160, v160, v156
	v_mul_f32_e32 v161, v161, v157
	v_fma_f32 v160, v160, v156, v156
	v_fma_f32 v161, v161, v157, v157
	v_mul_f32_e32 v160, 0x3f4c422a, v160
	v_mul_f32_e32 v161, 0x3f4c422a, v161
	v_mul_f32_e32 v160, -2.0, v160
	v_mul_f32_e32 v161, -2.0, v161
	v_mul_f32_e32 v160, 0x3fb8aa3b, v160
	v_mul_f32_e32 v161, 0x3fb8aa3b, v161
	v_exp_f32_e32 v160, v160
	v_exp_f32_e32 v161, v161
	v_add_f32_e32 v160, 1.0, v160
	v_add_f32_e32 v161, 1.0, v161
	v_rcp_f32_e32 v160, v160
	v_rcp_f32_e32 v161, v161
	v_mul_f32_e32 v160, v156, v160
	v_mul_f32_e32 v161, v157, v161
	v_mul_f32_e32 v158, v158, v160
	v_mul_f32_e32 v159, v159, v161
	v_cvt_pk_bf16_f32 v39, v158, v159
	global_store_dwordx4 v[2:3], v[36:39], off
	v_add_u32_e32 v1, 0xcd80, v138
	ds_read2_b32 v[148:149], v1 offset1:1
	v_add_u32_e32 v1, 0xcd88, v138
	ds_read2_b32 v[150:151], v1 offset1:1
	v_add_u32_e32 v1, 0xcd90, v138
	ds_read2_b32 v[152:153], v1 offset1:1
	v_add_u32_e32 v1, 0xcd98, v138
	ds_read2_b32 v[154:155], v1 offset1:1
	v_or_b32_e32 v2, s18, v95
	v_lshl_add_u32 v2, v2, 11, s61
	v_mov_b32_e32 v3, 0
	v_lshl_add_u64 v[2:3], v[78:79], 0, v[2:3]
	s_waitcnt vmcnt(0) lgkmcnt(0)
	v_lshlrev_b32_e32 v156, 16, v69
	v_and_b32_e32 v157, 0xffff0000, v69
	v_lshlrev_b32_e32 v158, 16, v250
	v_and_b32_e32 v159, 0xffff0000, v250
	v_add_f32_e32 v158, v158, v148
	v_add_f32_e32 v159, v159, v149
	v_mul_f32_e32 v160, 0x3d372713, v156
	v_mul_f32_e32 v161, 0x3d372713, v157
	v_mul_f32_e32 v160, v160, v156
	v_mul_f32_e32 v161, v161, v157
	v_fma_f32 v160, v160, v156, v156
	v_fma_f32 v161, v161, v157, v157
	v_mul_f32_e32 v160, 0x3f4c422a, v160
	v_mul_f32_e32 v161, 0x3f4c422a, v161
	v_mul_f32_e32 v160, -2.0, v160
	v_mul_f32_e32 v161, -2.0, v161
	v_mul_f32_e32 v160, 0x3fb8aa3b, v160
	v_mul_f32_e32 v161, 0x3fb8aa3b, v161
	v_exp_f32_e32 v160, v160
	v_exp_f32_e32 v161, v161
	v_add_f32_e32 v160, 1.0, v160
	v_add_f32_e32 v161, 1.0, v161
	v_rcp_f32_e32 v160, v160
	v_rcp_f32_e32 v161, v161
	v_mul_f32_e32 v160, v156, v160
	v_mul_f32_e32 v161, v157, v161
	v_mul_f32_e32 v158, v158, v160
	v_mul_f32_e32 v159, v159, v161
	v_cvt_pk_bf16_f32 v36, v158, v159
	v_lshlrev_b32_e32 v156, 16, v90
	v_and_b32_e32 v157, 0xffff0000, v90
	v_lshlrev_b32_e32 v158, 16, v251
	v_and_b32_e32 v159, 0xffff0000, v251
	v_add_f32_e32 v158, v158, v150
	v_add_f32_e32 v159, v159, v151
	v_mul_f32_e32 v160, 0x3d372713, v156
	v_mul_f32_e32 v161, 0x3d372713, v157
	v_mul_f32_e32 v160, v160, v156
	v_mul_f32_e32 v161, v161, v157
	v_fma_f32 v160, v160, v156, v156
	v_fma_f32 v161, v161, v157, v157
	v_mul_f32_e32 v160, 0x3f4c422a, v160
	v_mul_f32_e32 v161, 0x3f4c422a, v161
	v_mul_f32_e32 v160, -2.0, v160
	v_mul_f32_e32 v161, -2.0, v161
	v_mul_f32_e32 v160, 0x3fb8aa3b, v160
	v_mul_f32_e32 v161, 0x3fb8aa3b, v161
	v_exp_f32_e32 v160, v160
	v_exp_f32_e32 v161, v161
	v_add_f32_e32 v160, 1.0, v160
	v_add_f32_e32 v161, 1.0, v161
	v_rcp_f32_e32 v160, v160
	v_rcp_f32_e32 v161, v161
	v_mul_f32_e32 v160, v156, v160
	v_mul_f32_e32 v161, v157, v161
	v_mul_f32_e32 v158, v158, v160
	v_mul_f32_e32 v159, v159, v161
	v_cvt_pk_bf16_f32 v37, v158, v159
	v_lshlrev_b32_e32 v156, 16, v189
	v_and_b32_e32 v157, 0xffff0000, v189
	v_lshlrev_b32_e32 v158, 16, v252
	v_and_b32_e32 v159, 0xffff0000, v252
	v_add_f32_e32 v158, v158, v152
	v_add_f32_e32 v159, v159, v153
	v_mul_f32_e32 v160, 0x3d372713, v156
	v_mul_f32_e32 v161, 0x3d372713, v157
	v_mul_f32_e32 v160, v160, v156
	v_mul_f32_e32 v161, v161, v157
	v_fma_f32 v160, v160, v156, v156
	v_fma_f32 v161, v161, v157, v157
	v_mul_f32_e32 v160, 0x3f4c422a, v160
	v_mul_f32_e32 v161, 0x3f4c422a, v161
	v_mul_f32_e32 v160, -2.0, v160
	v_mul_f32_e32 v161, -2.0, v161
	v_mul_f32_e32 v160, 0x3fb8aa3b, v160
	v_mul_f32_e32 v161, 0x3fb8aa3b, v161
	v_exp_f32_e32 v160, v160
	v_exp_f32_e32 v161, v161
	v_add_f32_e32 v160, 1.0, v160
	v_add_f32_e32 v161, 1.0, v161
	v_rcp_f32_e32 v160, v160
	v_rcp_f32_e32 v161, v161
	v_mul_f32_e32 v160, v156, v160
	v_mul_f32_e32 v161, v157, v161
	v_mul_f32_e32 v158, v158, v160
	v_mul_f32_e32 v159, v159, v161
	v_cvt_pk_bf16_f32 v38, v158, v159
	v_lshlrev_b32_e32 v156, 16, v207
	v_and_b32_e32 v157, 0xffff0000, v207
	v_lshlrev_b32_e32 v158, 16, v253
	v_and_b32_e32 v159, 0xffff0000, v253
	v_add_f32_e32 v158, v158, v154
	v_add_f32_e32 v159, v159, v155
	v_mul_f32_e32 v160, 0x3d372713, v156
	v_mul_f32_e32 v161, 0x3d372713, v157
	v_mul_f32_e32 v160, v160, v156
	v_mul_f32_e32 v161, v161, v157
	v_fma_f32 v160, v160, v156, v156
	v_fma_f32 v161, v161, v157, v157
	v_mul_f32_e32 v160, 0x3f4c422a, v160
	v_mul_f32_e32 v161, 0x3f4c422a, v161
	v_mul_f32_e32 v160, -2.0, v160
	v_mul_f32_e32 v161, -2.0, v161
	v_mul_f32_e32 v160, 0x3fb8aa3b, v160
	v_mul_f32_e32 v161, 0x3fb8aa3b, v161
	v_exp_f32_e32 v160, v160
	v_exp_f32_e32 v161, v161
	v_add_f32_e32 v160, 1.0, v160
	v_add_f32_e32 v161, 1.0, v161
	v_rcp_f32_e32 v160, v160
	v_rcp_f32_e32 v161, v161
	v_mul_f32_e32 v160, v156, v160
	v_mul_f32_e32 v161, v157, v161
	v_mul_f32_e32 v158, v158, v160
	v_mul_f32_e32 v159, v159, v161
	v_cvt_pk_bf16_f32 v39, v158, v159
	global_store_dwordx4 v[2:3], v[36:39], off
.Lfg_join_p:
	s_cmp_eq_u32 s22, 4
	s_cbranch_scc1 .LBB0_275
	s_mov_b32 s34, s22
	s_branch .LBB0_256

.LBB0_290:
	s_or_b64 exec, exec, s[4:5]
	s_waitcnt lgkmcnt(0)
	s_barrier
	s_sub_i32 s15, 15, s20
	s_and_b64 s[4:5], s[12:13], exec
	s_cselect_b32 s4, s20, s15
	s_lshl_b32 s4, s4, 6
	s_add_i32 s4, s4, s34
	s_and_b64 s[98:99], s[12:13], exec
	s_mov_b32 s61, 0xd000000
	s_cselect_b32 s61, 0xf000000, s61
	s_cmp_lt_u32 s20, 8
	s_cbranch_scc0 .Lfg_out_s
	v_add_u32_e32 v1, 0xad00, v138
	ds_read2_b32 v[2:3], v1 offset1:1
	v_add_u32_e32 v1, 0xad08, v138
	ds_read2_b32 v[38:39], v1 offset1:1
	v_add_u32_e32 v1, 0xad10, v138
	ds_read2_b32 v[40:41], v1 offset1:1
	v_add_u32_e32 v1, 0xad18, v138
	ds_read2_b32 v[42:43], v1 offset1:1
	s_waitcnt lgkmcnt(3)
	v_cvt_pk_bf16_f32 v36, v2, v3
	v_or_b32_e32 v2, s4, v93
	v_ashrrev_i32_e32 v3, 31, v2
	v_lshlrev_b64 v[2:3], 11, v[2:3]
	s_waitcnt lgkmcnt(2)
	v_cvt_pk_bf16_f32 v37, v38, v39
	s_waitcnt lgkmcnt(1)
	v_cvt_pk_bf16_f32 v38, v40, v41
	s_waitcnt lgkmcnt(0)
	v_cvt_pk_bf16_f32 v39, v42, v43
	v_lshl_add_u64 v[2:3], v[78:79], 0, v[2:3]
	global_store_dwordx4 v[2:3], v[36:39], off
	v_add_u32_e32 v1, 0xcd80, v138
	ds_read2_b32 v[2:3], v1 offset1:1
	v_add_u32_e32 v1, 0xcd88, v138
	ds_read2_b32 v[38:39], v1 offset1:1
	v_add_u32_e32 v1, 0xcd90, v138
	ds_read2_b32 v[40:41], v1 offset1:1
	v_add_u32_e32 v1, 0xcd98, v138
	ds_read2_b32 v[42:43], v1 offset1:1
	s_waitcnt lgkmcnt(3)
	v_cvt_pk_bf16_f32 v36, v2, v3
	v_or_b32_e32 v2, s4, v95
	v_ashrrev_i32_e32 v3, 31, v2
	v_lshlrev_b64 v[2:3], 11, v[2:3]
	s_waitcnt lgkmcnt(2)
	v_cvt_pk_bf16_f32 v37, v38, v39
	s_waitcnt lgkmcnt(1)
	v_cvt_pk_bf16_f32 v38, v40, v41
	s_waitcnt lgkmcnt(0)
	v_cvt_pk_bf16_f32 v39, v42, v43
	v_lshl_add_u64 v[2:3], v[78:79], 0, v[2:3]
	global_store_dwordx4 v[2:3], v[36:39], off
	s_branch .Lfg_join_s
.Lfg_out_s:
	v_add_u32_e32 v1, 0xad00, v138
	ds_read2_b32 v[148:149], v1 offset1:1
	v_add_u32_e32 v1, 0xad08, v138
	ds_read2_b32 v[150:151], v1 offset1:1
	v_add_u32_e32 v1, 0xad10, v138
	ds_read2_b32 v[152:153], v1 offset1:1
	v_add_u32_e32 v1, 0xad18, v138
	ds_read2_b32 v[154:155], v1 offset1:1
	v_or_b32_e32 v2, s4, v93
	v_lshl_add_u32 v2, v2, 11, s61
	v_mov_b32_e32 v3, 0
	v_lshl_add_u64 v[2:3], v[78:79], 0, v[2:3]
	s_waitcnt vmcnt(0) lgkmcnt(0)
	v_lshlrev_b32_e32 v156, 16, v238
	v_and_b32_e32 v157, 0xffff0000, v238
	v_lshlrev_b32_e32 v158, 16, v228
	v_and_b32_e32 v159, 0xffff0000, v228
	v_add_f32_e32 v158, v158, v148
	v_add_f32_e32 v159, v159, v149
	v_mul_f32_e32 v160, 0x3d372713, v156
	v_mul_f32_e32 v161, 0x3d372713, v157
	v_mul_f32_e32 v160, v160, v156
	v_mul_f32_e32 v161, v161, v157
	v_fma_f32 v160, v160, v156, v156
	v_fma_f32 v161, v161, v157, v157
	v_mul_f32_e32 v160, 0x3f4c422a, v160
	v_mul_f32_e32 v161, 0x3f4c422a, v161
	v_mul_f32_e32 v160, -2.0, v160
	v_mul_f32_e32 v161, -2.0, v161
	v_mul_f32_e32 v160, 0x3fb8aa3b, v160
	v_mul_f32_e32 v161, 0x3fb8aa3b, v161
	v_exp_f32_e32 v160, v160
	v_exp_f32_e32 v161, v161
	v_add_f32_e32 v160, 1.0, v160
	v_add_f32_e32 v161, 1.0, v161
	v_rcp_f32_e32 v160, v160
	v_rcp_f32_e32 v161, v161
	v_mul_f32_e32 v160, v156, v160
	v_mul_f32_e32 v161, v157, v161
	v_mul_f32_e32 v158, v158, v160
	v_mul_f32_e32 v159, v159, v161
	v_cvt_pk_bf16_f32 v36, v158, v159
	v_lshlrev_b32_e32 v156, 16, v239
	v_and_b32_e32 v157, 0xffff0000, v239
	v_lshlrev_b32_e32 v158, 16, v229
	v_and_b32_e32 v159, 0xffff0000, v229
	v_add_f32_e32 v158, v158, v150
	v_add_f32_e32 v159, v159, v151
	v_mul_f32_e32 v160, 0x3d372713, v156
	v_mul_f32_e32 v161, 0x3d372713, v157
	v_mul_f32_e32 v160, v160, v156
	v_mul_f32_e32 v161, v161, v157
	v_fma_f32 v160, v160, v156, v156
	v_fma_f32 v161, v161, v157, v157
	v_mul_f32_e32 v160, 0x3f4c422a, v160
	v_mul_f32_e32 v161, 0x3f4c422a, v161
	v_mul_f32_e32 v160, -2.0, v160
	v_mul_f32_e32 v161, -2.0, v161
	v_mul_f32_e32 v160, 0x3fb8aa3b, v160
	v_mul_f32_e32 v161, 0x3fb8aa3b, v161
	v_exp_f32_e32 v160, v160
	v_exp_f32_e32 v161, v161
	v_add_f32_e32 v160, 1.0, v160
	v_add_f32_e32 v161, 1.0, v161
	v_rcp_f32_e32 v160, v160
	v_rcp_f32_e32 v161, v161
	v_mul_f32_e32 v160, v156, v160
	v_mul_f32_e32 v161, v157, v161
	v_mul_f32_e32 v158, v158, v160
	v_mul_f32_e32 v159, v159, v161
	v_cvt_pk_bf16_f32 v37, v158, v159
	v_lshlrev_b32_e32 v156, 16, v240
	v_and_b32_e32 v157, 0xffff0000, v240
	v_lshlrev_b32_e32 v158, 16, v230
	v_and_b32_e32 v159, 0xffff0000, v230
	v_add_f32_e32 v158, v158, v152
	v_add_f32_e32 v159, v159, v153
	v_mul_f32_e32 v160, 0x3d372713, v156
	v_mul_f32_e32 v161, 0x3d372713, v157
	v_mul_f32_e32 v160, v160, v156
	v_mul_f32_e32 v161, v161, v157
	v_fma_f32 v160, v160, v156, v156
	v_fma_f32 v161, v161, v157, v157
	v_mul_f32_e32 v160, 0x3f4c422a, v160
	v_mul_f32_e32 v161, 0x3f4c422a, v161
	v_mul_f32_e32 v160, -2.0, v160
	v_mul_f32_e32 v161, -2.0, v161
	v_mul_f32_e32 v160, 0x3fb8aa3b, v160
	v_mul_f32_e32 v161, 0x3fb8aa3b, v161
	v_exp_f32_e32 v160, v160
	v_exp_f32_e32 v161, v161
	v_add_f32_e32 v160, 1.0, v160
	v_add_f32_e32 v161, 1.0, v161
	v_rcp_f32_e32 v160, v160
	v_rcp_f32_e32 v161, v161
	v_mul_f32_e32 v160, v156, v160
	v_mul_f32_e32 v161, v157, v161
	v_mul_f32_e32 v158, v158, v160
	v_mul_f32_e32 v159, v159, v161
	v_cvt_pk_bf16_f32 v38, v158, v159
	v_lshlrev_b32_e32 v156, 16, v241
	v_and_b32_e32 v157, 0xffff0000, v241
	v_lshlrev_b32_e32 v158, 16, v231
	v_and_b32_e32 v159, 0xffff0000, v231
	v_add_f32_e32 v158, v158, v154
	v_add_f32_e32 v159, v159, v155
	v_mul_f32_e32 v160, 0x3d372713, v156
	v_mul_f32_e32 v161, 0x3d372713, v157
	v_mul_f32_e32 v160, v160, v156
	v_mul_f32_e32 v161, v161, v157
	v_fma_f32 v160, v160, v156, v156
	v_fma_f32 v161, v161, v157, v157
	v_mul_f32_e32 v160, 0x3f4c422a, v160
	v_mul_f32_e32 v161, 0x3f4c422a, v161
	v_mul_f32_e32 v160, -2.0, v160
	v_mul_f32_e32 v161, -2.0, v161
	v_mul_f32_e32 v160, 0x3fb8aa3b, v160
	v_mul_f32_e32 v161, 0x3fb8aa3b, v161
	v_exp_f32_e32 v160, v160
	v_exp_f32_e32 v161, v161
	v_add_f32_e32 v160, 1.0, v160
	v_add_f32_e32 v161, 1.0, v161
	v_rcp_f32_e32 v160, v160
	v_rcp_f32_e32 v161, v161
	v_mul_f32_e32 v160, v156, v160
	v_mul_f32_e32 v161, v157, v161
	v_mul_f32_e32 v158, v158, v160
	v_mul_f32_e32 v159, v159, v161
	v_cvt_pk_bf16_f32 v39, v158, v159
	global_store_dwordx4 v[2:3], v[36:39], off
	v_add_u32_e32 v1, 0xcd80, v138
	ds_read2_b32 v[148:149], v1 offset1:1
	v_add_u32_e32 v1, 0xcd88, v138
	ds_read2_b32 v[150:151], v1 offset1:1
	v_add_u32_e32 v1, 0xcd90, v138
	ds_read2_b32 v[152:153], v1 offset1:1
	v_add_u32_e32 v1, 0xcd98, v138
	ds_read2_b32 v[154:155], v1 offset1:1
	v_or_b32_e32 v2, s4, v95
	v_lshl_add_u32 v2, v2, 11, s61
	v_mov_b32_e32 v3, 0
	v_lshl_add_u64 v[2:3], v[78:79], 0, v[2:3]
	s_waitcnt vmcnt(0) lgkmcnt(0)
	v_lshlrev_b32_e32 v156, 16, v69
	v_and_b32_e32 v157, 0xffff0000, v69
	v_lshlrev_b32_e32 v158, 16, v250
	v_and_b32_e32 v159, 0xffff0000, v250
	v_add_f32_e32 v158, v158, v148
	v_add_f32_e32 v159, v159, v149
	v_mul_f32_e32 v160, 0x3d372713, v156
	v_mul_f32_e32 v161, 0x3d372713, v157
	v_mul_f32_e32 v160, v160, v156
	v_mul_f32_e32 v161, v161, v157
	v_fma_f32 v160, v160, v156, v156
	v_fma_f32 v161, v161, v157, v157
	v_mul_f32_e32 v160, 0x3f4c422a, v160
	v_mul_f32_e32 v161, 0x3f4c422a, v161
	v_mul_f32_e32 v160, -2.0, v160
	v_mul_f32_e32 v161, -2.0, v161
	v_mul_f32_e32 v160, 0x3fb8aa3b, v160
	v_mul_f32_e32 v161, 0x3fb8aa3b, v161
	v_exp_f32_e32 v160, v160
	v_exp_f32_e32 v161, v161
	v_add_f32_e32 v160, 1.0, v160
	v_add_f32_e32 v161, 1.0, v161
	v_rcp_f32_e32 v160, v160
	v_rcp_f32_e32 v161, v161
	v_mul_f32_e32 v160, v156, v160
	v_mul_f32_e32 v161, v157, v161
	v_mul_f32_e32 v158, v158, v160
	v_mul_f32_e32 v159, v159, v161
	v_cvt_pk_bf16_f32 v36, v158, v159
	v_lshlrev_b32_e32 v156, 16, v90
	v_and_b32_e32 v157, 0xffff0000, v90
	v_lshlrev_b32_e32 v158, 16, v251
	v_and_b32_e32 v159, 0xffff0000, v251
	v_add_f32_e32 v158, v158, v150
	v_add_f32_e32 v159, v159, v151
	v_mul_f32_e32 v160, 0x3d372713, v156
	v_mul_f32_e32 v161, 0x3d372713, v157
	v_mul_f32_e32 v160, v160, v156
	v_mul_f32_e32 v161, v161, v157
	v_fma_f32 v160, v160, v156, v156
	v_fma_f32 v161, v161, v157, v157
	v_mul_f32_e32 v160, 0x3f4c422a, v160
	v_mul_f32_e32 v161, 0x3f4c422a, v161
	v_mul_f32_e32 v160, -2.0, v160
	v_mul_f32_e32 v161, -2.0, v161
	v_mul_f32_e32 v160, 0x3fb8aa3b, v160
	v_mul_f32_e32 v161, 0x3fb8aa3b, v161
	v_exp_f32_e32 v160, v160
	v_exp_f32_e32 v161, v161
	v_add_f32_e32 v160, 1.0, v160
	v_add_f32_e32 v161, 1.0, v161
	v_rcp_f32_e32 v160, v160
	v_rcp_f32_e32 v161, v161
	v_mul_f32_e32 v160, v156, v160
	v_mul_f32_e32 v161, v157, v161
	v_mul_f32_e32 v158, v158, v160
	v_mul_f32_e32 v159, v159, v161
	v_cvt_pk_bf16_f32 v37, v158, v159
	v_lshlrev_b32_e32 v156, 16, v189
	v_and_b32_e32 v157, 0xffff0000, v189
	v_lshlrev_b32_e32 v158, 16, v252
	v_and_b32_e32 v159, 0xffff0000, v252
	v_add_f32_e32 v158, v158, v152
	v_add_f32_e32 v159, v159, v153
	v_mul_f32_e32 v160, 0x3d372713, v156
	v_mul_f32_e32 v161, 0x3d372713, v157
	v_mul_f32_e32 v160, v160, v156
	v_mul_f32_e32 v161, v161, v157
	v_fma_f32 v160, v160, v156, v156
	v_fma_f32 v161, v161, v157, v157
	v_mul_f32_e32 v160, 0x3f4c422a, v160
	v_mul_f32_e32 v161, 0x3f4c422a, v161
	v_mul_f32_e32 v160, -2.0, v160
	v_mul_f32_e32 v161, -2.0, v161
	v_mul_f32_e32 v160, 0x3fb8aa3b, v160
	v_mul_f32_e32 v161, 0x3fb8aa3b, v161
	v_exp_f32_e32 v160, v160
	v_exp_f32_e32 v161, v161
	v_add_f32_e32 v160, 1.0, v160
	v_add_f32_e32 v161, 1.0, v161
	v_rcp_f32_e32 v160, v160
	v_rcp_f32_e32 v161, v161
	v_mul_f32_e32 v160, v156, v160
	v_mul_f32_e32 v161, v157, v161
	v_mul_f32_e32 v158, v158, v160
	v_mul_f32_e32 v159, v159, v161
	v_cvt_pk_bf16_f32 v38, v158, v159
	v_lshlrev_b32_e32 v156, 16, v207
	v_and_b32_e32 v157, 0xffff0000, v207
	v_lshlrev_b32_e32 v158, 16, v253
	v_and_b32_e32 v159, 0xffff0000, v253
	v_add_f32_e32 v158, v158, v154
	v_add_f32_e32 v159, v159, v155
	v_mul_f32_e32 v160, 0x3d372713, v156
	v_mul_f32_e32 v161, 0x3d372713, v157
	v_mul_f32_e32 v160, v160, v156
	v_mul_f32_e32 v161, v161, v157
	v_fma_f32 v160, v160, v156, v156
	v_fma_f32 v161, v161, v157, v157
	v_mul_f32_e32 v160, 0x3f4c422a, v160
	v_mul_f32_e32 v161, 0x3f4c422a, v161
	v_mul_f32_e32 v160, -2.0, v160
	v_mul_f32_e32 v161, -2.0, v161
	v_mul_f32_e32 v160, 0x3fb8aa3b, v160
	v_mul_f32_e32 v161, 0x3fb8aa3b, v161
	v_exp_f32_e32 v160, v160
	v_exp_f32_e32 v161, v161
	v_add_f32_e32 v160, 1.0, v160
	v_add_f32_e32 v161, 1.0, v161
	v_rcp_f32_e32 v160, v160
	v_rcp_f32_e32 v161, v161
	v_mul_f32_e32 v160, v156, v160
	v_mul_f32_e32 v161, v157, v161
	v_mul_f32_e32 v158, v158, v160
	v_mul_f32_e32 v159, v159, v161
	v_cvt_pk_bf16_f32 v39, v158, v159
	global_store_dwordx4 v[2:3], v[36:39], off
.Lfg_join_s:
	s_cmp_eq_u32 s14, 16
	s_mov_b32 s20, s14
	s_cbranch_scc1 .LBB0_245

.LBB0_305:
	s_waitcnt lgkmcnt(0)
	s_barrier
	ds_read_b128 v[40:43], v117
	ds_read_b128 v[36:39], v117 offset:64
	ds_read_b128 v[44:47], v118 offset:9216
	ds_read_b128 v[48:51], v118 offset:18432
	ds_read_b128 v[52:55], v118 offset:9280
	s_waitcnt lgkmcnt(2)
	v_mfma_f32_16x16x32_bf16 v[44:47], v[40:43], v[44:47], 0
	ds_read_u16 v3, v119
	s_waitcnt lgkmcnt(0)
	v_lshlrev_b32_e32 v3, 16, v3
	v_mfma_f32_16x16x32_bf16 v[44:47], v[36:39], v[52:55], v[44:47]
	ds_read_b128 v[52:55], v118 offset:18496
	v_mfma_f32_16x16x32_bf16 v[48:51], v[40:43], v[48:51], 0
	s_waitcnt lgkmcnt(0)
	v_mfma_f32_16x16x32_bf16 v[48:51], v[36:39], v[52:55], v[48:51]
	s_nop 3
	v_add_f32_e32 v1, v97, v44
	v_mul_f32_e32 v1, 0xbfb8aa3b, v1
	v_exp_f32_e32 v1, v1
	s_nop 0
	v_add_f32_e32 v1, 1.0, v1
	v_rcp_f32_e32 v1, v1
	v_add_f32_e32 v2, v98, v48
	v_mul_f32_e32 v2, 0xbfb8aa3b, v2
	v_exp_f32_e32 v2, v2
	v_mul_f32_e32 v1, v105, v1
	v_mul_f32_e32 v1, 0x3fb8aa3b, v1
	v_exp_f32_e32 v1, v1
	v_add_f32_e32 v2, 1.0, v2
	v_rcp_f32_e32 v2, v2
	v_fma_f32 v44, -v1, v1, 1.0
	v_max_f32_e32 v44, 0, v44
	v_sqrt_f32_e32 v44, v44
	v_mul_f32_e32 v2, v2, v3
	v_mul_f32_e32 v2, v2, v44
	ds_write_b32 v109, v1 offset:27648
	ds_write_b32 v109, v2 offset:44288
	v_add_f32_e32 v1, v97, v45
	v_mul_f32_e32 v1, 0xbfb8aa3b, v1
	v_exp_f32_e32 v1, v1
	v_add_f32_e32 v2, v98, v49
	v_mul_f32_e32 v2, 0xbfb8aa3b, v2
	v_exp_f32_e32 v2, v2
	v_add_f32_e32 v1, 1.0, v1
	v_rcp_f32_e32 v1, v1
	ds_read_u16 v3, v120
	v_add_f32_e32 v2, 1.0, v2
	v_rcp_f32_e32 v2, v2
	v_mul_f32_e32 v1, v105, v1
	v_mul_f32_e32 v1, 0x3fb8aa3b, v1
	v_exp_f32_e32 v1, v1
	s_waitcnt lgkmcnt(0)
	v_lshlrev_b32_e32 v3, 16, v3
	v_mul_f32_e32 v2, v2, v3
	ds_read_u16 v3, v121
	v_fma_f32 v44, -v1, v1, 1.0
	v_max_f32_e32 v44, 0, v44
	v_sqrt_f32_e32 v44, v44
	s_waitcnt lgkmcnt(0)
	v_lshlrev_b32_e32 v3, 16, v3
	v_mul_f32_e32 v2, v2, v44
	ds_write2st64_b32 v110, v1, v2 offset0:108 offset1:173
	v_add_f32_e32 v1, v97, v46
	v_mul_f32_e32 v1, 0xbfb8aa3b, v1
	v_exp_f32_e32 v1, v1
	v_add_f32_e32 v2, v98, v50
	v_mul_f32_e32 v2, 0xbfb8aa3b, v2
	v_exp_f32_e32 v2, v2
	v_add_f32_e32 v1, 1.0, v1
	v_rcp_f32_e32 v1, v1
	v_add_f32_e32 v2, 1.0, v2
	v_rcp_f32_e32 v2, v2
	v_mul_f32_e32 v1, v105, v1
	v_mul_f32_e32 v1, 0x3fb8aa3b, v1
	v_exp_f32_e32 v1, v1
	v_mul_f32_e32 v2, v2, v3
	v_fma_f32 v44, -v1, v1, 1.0
	v_max_f32_e32 v44, 0, v44
	v_sqrt_f32_e32 v44, v44
	s_nop 0
	v_mul_f32_e32 v2, v2, v44
	ds_write_b32 v111, v1 offset:27648
	ds_write_b32 v111, v2 offset:44288
	v_add_f32_e32 v1, v97, v47
	v_mul_f32_e32 v1, 0xbfb8aa3b, v1
	v_exp_f32_e32 v1, v1
	v_add_f32_e32 v2, v98, v51
	v_mul_f32_e32 v2, 0xbfb8aa3b, v2
	v_exp_f32_e32 v2, v2
	v_add_f32_e32 v1, 1.0, v1
	v_rcp_f32_e32 v1, v1
	ds_read_u16 v3, v122
	v_add_f32_e32 v2, 1.0, v2
	v_rcp_f32_e32 v2, v2
	v_mul_f32_e32 v1, v105, v1
	v_mul_f32_e32 v1, 0x3fb8aa3b, v1
	v_exp_f32_e32 v1, v1
	s_waitcnt lgkmcnt(0)
	v_lshlrev_b32_e32 v3, 16, v3
	v_mul_f32_e32 v2, v2, v3
	ds_read_u16 v3, v124
	v_fma_f32 v44, -v1, v1, 1.0
	v_max_f32_e32 v44, 0, v44
	v_sqrt_f32_e32 v44, v44
	s_waitcnt lgkmcnt(0)
	v_lshlrev_b32_e32 v3, 16, v3
	v_mul_f32_e32 v2, v44, v2
	ds_write2st64_b32 v112, v1, v2 offset0:108 offset1:173
	ds_read_b128 v[48:51], v123 offset:18432
	ds_read_b128 v[44:47], v123 offset:9216
	s_waitcnt lgkmcnt(1)
	v_mfma_f32_16x16x32_bf16 v[52:55], v[40:43], v[48:51], 0
	ds_read_b128 v[48:51], v123 offset:9280
	s_waitcnt lgkmcnt(1)
	v_mfma_f32_16x16x32_bf16 v[44:47], v[40:43], v[44:47], 0
	s_waitcnt lgkmcnt(0)
	v_mfma_f32_16x16x32_bf16 v[48:51], v[36:39], v[48:51], v[44:47]
	s_nop 5
	ds_read_b128 v[44:47], v123 offset:18496
	s_nop 0
	v_add_f32_e32 v1, v99, v48
	v_mul_f32_e32 v1, 0xbfb8aa3b, v1
	v_exp_f32_e32 v1, v1
	s_waitcnt lgkmcnt(0)
	v_mfma_f32_16x16x32_bf16 v[44:47], v[36:39], v[44:47], v[52:55]
	v_add_f32_e32 v1, 1.0, v1
	v_rcp_f32_e32 v1, v1
	s_nop 0
	v_mul_f32_e32 v1, v106, v1
	s_nop 3
	v_add_f32_e32 v2, v100, v44
	v_mul_f32_e32 v2, 0xbfb8aa3b, v2
	v_mul_f32_e32 v1, 0x3fb8aa3b, v1
	v_exp_f32_e32 v2, v2
	v_exp_f32_e32 v1, v1
	v_add_f32_e32 v2, 1.0, v2
	v_fma_f32 v44, -v1, v1, 1.0
	v_rcp_f32_e32 v2, v2
	v_max_f32_e32 v44, 0, v44
	v_sqrt_f32_e32 v44, v44
	v_mul_f32_e32 v2, v2, v3
	v_mul_f32_e32 v2, v2, v44
	ds_write_b32 v109, v1 offset:27712
	ds_write_b32 v109, v2 offset:44352
	v_add_f32_e32 v1, v99, v49
	v_mul_f32_e32 v1, 0xbfb8aa3b, v1
	v_exp_f32_e32 v1, v1
	v_add_f32_e32 v2, v100, v45
	v_mul_f32_e32 v2, 0xbfb8aa3b, v2
	v_exp_f32_e32 v2, v2
	v_add_f32_e32 v1, 1.0, v1
	v_rcp_f32_e32 v1, v1
	ds_read_u16 v3, v125
	v_add_f32_e32 v2, 1.0, v2
	v_rcp_f32_e32 v2, v2
	v_mul_f32_e32 v1, v106, v1
	v_mul_f32_e32 v1, 0x3fb8aa3b, v1
	v_exp_f32_e32 v1, v1
	s_waitcnt lgkmcnt(0)
	v_lshlrev_b32_e32 v3, 16, v3
	v_mul_f32_e32 v2, v2, v3
	v_fma_f32 v44, -v1, v1, 1.0
	v_max_f32_e32 v44, 0, v44
	v_sqrt_f32_e32 v44, v44
	s_nop 0
	v_mul_f32_e32 v2, v2, v44
	ds_write_b32 v113, v1 offset:27712
	ds_write_b32 v113, v2 offset:44352
	v_add_f32_e32 v1, v99, v50
	v_mul_f32_e32 v1, 0xbfb8aa3b, v1
	v_exp_f32_e32 v1, v1
	v_add_f32_e32 v2, v100, v46
	v_mul_f32_e32 v2, 0xbfb8aa3b, v2
	v_exp_f32_e32 v2, v2
	v_add_f32_e32 v1, 1.0, v1
	v_rcp_f32_e32 v1, v1
	ds_read_u16 v3, v126
	v_add_f32_e32 v2, 1.0, v2
	v_rcp_f32_e32 v2, v2
	v_mul_f32_e32 v1, v106, v1
	v_mul_f32_e32 v1, 0x3fb8aa3b, v1
	v_exp_f32_e32 v1, v1
	s_waitcnt lgkmcnt(0)
	v_lshlrev_b32_e32 v3, 16, v3
	v_mul_f32_e32 v2, v2, v3
	v_fma_f32 v44, -v1, v1, 1.0
	v_max_f32_e32 v44, 0, v44
	v_sqrt_f32_e32 v44, v44
	s_nop 0
	v_mul_f32_e32 v2, v2, v44
	ds_write_b32 v111, v1 offset:27712
	ds_write_b32 v111, v2 offset:44352
	v_add_f32_e32 v1, v99, v51
	v_mul_f32_e32 v1, 0xbfb8aa3b, v1
	v_exp_f32_e32 v1, v1
	ds_read_u16 v3, v127
	v_add_f32_e32 v1, 1.0, v1
	v_rcp_f32_e32 v2, v1
	v_add_f32_e32 v1, v100, v47
	v_mul_f32_e32 v1, 0xbfb8aa3b, v1
	v_exp_f32_e32 v1, v1
	v_mul_f32_e32 v2, v106, v2
	v_mul_f32_e32 v2, 0x3fb8aa3b, v2
	v_exp_f32_e32 v2, v2
	v_add_f32_e32 v1, 1.0, v1
	v_rcp_f32_e32 v1, v1
	s_waitcnt lgkmcnt(0)
	v_lshlrev_b32_e32 v3, 16, v3
	v_fma_f32 v44, -v2, v2, 1.0
	v_max_f32_e32 v44, 0, v44
	v_sqrt_f32_e32 v44, v44
	v_mul_f32_e32 v1, v1, v3
	v_mul_f32_e32 v1, v44, v1
	ds_write_b32 v114, v2 offset:27712
	ds_write_b32 v114, v1 offset:44352
	ds_read_b128 v[44:47], v128 offset:9216
	ds_read_b128 v[52:55], v128 offset:9280
	s_waitcnt lgkmcnt(1)
	v_mfma_f32_16x16x32_bf16 v[44:47], v[40:43], v[44:47], 0
	ds_read_b128 v[48:51], v128 offset:18432
	ds_read_u16 v3, v129
	s_waitcnt lgkmcnt(0)
	v_lshlrev_b32_e32 v3, 16, v3
	v_mfma_f32_16x16x32_bf16 v[44:47], v[36:39], v[52:55], v[44:47]
	ds_read_b128 v[52:55], v128 offset:18496
	v_mfma_f32_16x16x32_bf16 v[48:51], v[40:43], v[48:51], 0
	s_waitcnt lgkmcnt(0)
	v_mfma_f32_16x16x32_bf16 v[48:51], v[36:39], v[52:55], v[48:51]
	s_nop 3
	v_add_f32_e32 v1, v101, v44
	v_mul_f32_e32 v1, 0xbfb8aa3b, v1
	v_exp_f32_e32 v1, v1
	s_nop 0
	v_add_f32_e32 v1, 1.0, v1
	v_rcp_f32_e32 v1, v1
	v_add_f32_e32 v2, v102, v48
	v_mul_f32_e32 v2, 0xbfb8aa3b, v2
	v_exp_f32_e32 v2, v2
	v_mul_f32_e32 v1, v107, v1
	v_mul_f32_e32 v1, 0x3fb8aa3b, v1
	v_exp_f32_e32 v1, v1
	v_add_f32_e32 v2, 1.0, v2
	v_rcp_f32_e32 v2, v2
	v_fma_f32 v44, -v1, v1, 1.0
	v_max_f32_e32 v44, 0, v44
	v_sqrt_f32_e32 v44, v44
	v_mul_f32_e32 v2, v2, v3
	v_mul_f32_e32 v2, v2, v44
	ds_write_b32 v109, v1 offset:27776
	ds_write_b32 v109, v2 offset:44416
	v_add_f32_e32 v1, v101, v45
	v_mul_f32_e32 v1, 0xbfb8aa3b, v1
	v_exp_f32_e32 v1, v1
	v_add_f32_e32 v2, v102, v49
	v_mul_f32_e32 v2, 0xbfb8aa3b, v2
	v_exp_f32_e32 v2, v2
	v_add_f32_e32 v1, 1.0, v1
	v_rcp_f32_e32 v1, v1
	ds_read_u16 v3, v130
	v_add_f32_e32 v2, 1.0, v2
	v_rcp_f32_e32 v2, v2
	v_mul_f32_e32 v1, v107, v1
	v_mul_f32_e32 v1, 0x3fb8aa3b, v1
	v_exp_f32_e32 v1, v1
	s_waitcnt lgkmcnt(0)
	v_lshlrev_b32_e32 v3, 16, v3
	v_mul_f32_e32 v2, v2, v3
	v_fma_f32 v44, -v1, v1, 1.0
	v_max_f32_e32 v44, 0, v44
	v_sqrt_f32_e32 v44, v44
	s_nop 0
	v_mul_f32_e32 v2, v2, v44
	ds_write_b32 v113, v1 offset:27776
	ds_write_b32 v113, v2 offset:44416
	v_add_f32_e32 v1, v101, v46
	v_mul_f32_e32 v1, 0xbfb8aa3b, v1
	v_exp_f32_e32 v1, v1
	v_add_f32_e32 v2, v102, v50
	v_mul_f32_e32 v2, 0xbfb8aa3b, v2
	v_exp_f32_e32 v2, v2
	v_add_f32_e32 v1, 1.0, v1
	v_rcp_f32_e32 v1, v1
	ds_read_u16 v3, v131
	v_add_f32_e32 v2, 1.0, v2
	v_rcp_f32_e32 v2, v2
	v_mul_f32_e32 v1, v107, v1
	v_mul_f32_e32 v1, 0x3fb8aa3b, v1
	v_exp_f32_e32 v1, v1
	s_waitcnt lgkmcnt(0)
	v_lshlrev_b32_e32 v3, 16, v3
	v_mul_f32_e32 v2, v2, v3
	v_fma_f32 v44, -v1, v1, 1.0
	v_max_f32_e32 v44, 0, v44
	v_sqrt_f32_e32 v44, v44
	s_nop 0
	v_mul_f32_e32 v2, v2, v44
	ds_write_b32 v111, v1 offset:27776
	ds_write_b32 v111, v2 offset:44416
	v_add_f32_e32 v1, v101, v47
	v_mul_f32_e32 v1, 0xbfb8aa3b, v1
	v_exp_f32_e32 v1, v1
	v_add_f32_e32 v2, v102, v51
	v_mul_f32_e32 v2, 0xbfb8aa3b, v2
	v_exp_f32_e32 v2, v2
	v_add_f32_e32 v1, 1.0, v1
	v_rcp_f32_e32 v1, v1
	ds_read_u16 v3, v132
	v_add_f32_e32 v2, 1.0, v2
	v_rcp_f32_e32 v2, v2
	v_mul_f32_e32 v1, v107, v1
	v_mul_f32_e32 v1, 0x3fb8aa3b, v1
	v_exp_f32_e32 v1, v1
	s_waitcnt lgkmcnt(0)
	v_lshlrev_b32_e32 v3, 16, v3
	v_mul_f32_e32 v2, v2, v3
	v_fma_f32 v44, -v1, v1, 1.0
	v_max_f32_e32 v44, 0, v44
	v_sqrt_f32_e32 v44, v44
	s_nop 0
	v_mul_f32_e32 v2, v44, v2
	ds_write_b32 v114, v1 offset:27776
	ds_write_b32 v114, v2 offset:44416
	ds_read_b128 v[44:47], v133 offset:9216
	ds_read_b128 v[48:51], v133 offset:18432
	s_waitcnt lgkmcnt(1)
	v_mfma_f32_16x16x32_bf16 v[44:47], v[40:43], v[44:47], 0
	ds_read_u16 v3, v134
	s_waitcnt lgkmcnt(0)
	v_lshlrev_b32_e32 v3, 16, v3
	v_mfma_f32_16x16x32_bf16 v[48:51], v[40:43], v[48:51], 0
	ds_read_b128 v[40:43], v133 offset:9280
	s_waitcnt lgkmcnt(0)
	v_mfma_f32_16x16x32_bf16 v[40:43], v[36:39], v[40:43], v[44:47]
	s_nop 2
	ds_read_b128 v[44:47], v133 offset:18496
	s_waitcnt lgkmcnt(0)
	v_mfma_f32_16x16x32_bf16 v[36:39], v[36:39], v[44:47], v[48:51]
	s_nop 1
	v_add_f32_e32 v1, v103, v40
	v_mul_f32_e32 v1, 0xbfb8aa3b, v1
	v_exp_f32_e32 v1, v1
	s_nop 2
	v_add_f32_e32 v2, v104, v36
	v_mul_f32_e32 v2, 0xbfb8aa3b, v2
	v_exp_f32_e32 v2, v2
	v_add_f32_e32 v1, 1.0, v1
	v_rcp_f32_e32 v1, v1
	v_add_f32_e32 v2, 1.0, v2
	v_rcp_f32_e32 v2, v2
	v_mul_f32_e32 v1, v108, v1
	v_mul_f32_e32 v1, 0x3fb8aa3b, v1
	v_exp_f32_e32 v1, v1
	v_mul_f32_e32 v2, v2, v3
	v_fma_f32 v36, -v1, v1, 1.0
	v_max_f32_e32 v36, 0, v36
	v_sqrt_f32_e32 v36, v36
	s_nop 0
	v_mul_f32_e32 v2, v2, v36
	ds_write_b32 v109, v1 offset:27840
	ds_write_b32 v109, v2 offset:44480
	v_add_f32_e32 v1, v103, v41
	v_mul_f32_e32 v1, 0xbfb8aa3b, v1
	v_exp_f32_e32 v1, v1
	v_add_f32_e32 v2, v104, v37
	v_mul_f32_e32 v2, 0xbfb8aa3b, v2
	v_exp_f32_e32 v2, v2
	v_add_f32_e32 v1, 1.0, v1
	v_rcp_f32_e32 v1, v1
	ds_read_u16 v3, v135
	v_add_f32_e32 v2, 1.0, v2
	v_rcp_f32_e32 v2, v2
	v_mul_f32_e32 v1, v108, v1
	v_mul_f32_e32 v1, 0x3fb8aa3b, v1
	v_exp_f32_e32 v1, v1
	s_waitcnt lgkmcnt(0)
	v_lshlrev_b32_e32 v3, 16, v3
	v_mul_f32_e32 v2, v2, v3
	v_fma_f32 v36, -v1, v1, 1.0
	v_max_f32_e32 v36, 0, v36
	v_sqrt_f32_e32 v36, v36
	s_nop 0
	v_mul_f32_e32 v2, v2, v36
	ds_write_b32 v113, v1 offset:27840
	ds_write_b32 v113, v2 offset:44480
	v_add_f32_e32 v1, v103, v42
	v_mul_f32_e32 v1, 0xbfb8aa3b, v1
	v_exp_f32_e32 v1, v1
	v_add_f32_e32 v2, v104, v38
	v_mul_f32_e32 v2, 0xbfb8aa3b, v2
	v_exp_f32_e32 v2, v2
	v_add_f32_e32 v1, 1.0, v1
	v_rcp_f32_e32 v1, v1
	ds_read_u16 v3, v136
	v_add_f32_e32 v2, 1.0, v2
	v_rcp_f32_e32 v2, v2
	v_mul_f32_e32 v1, v108, v1
	v_mul_f32_e32 v1, 0x3fb8aa3b, v1
	v_exp_f32_e32 v1, v1
	s_waitcnt lgkmcnt(0)
	v_lshlrev_b32_e32 v3, 16, v3
	v_mul_f32_e32 v2, v2, v3
	v_fma_f32 v36, -v1, v1, 1.0
	v_max_f32_e32 v36, 0, v36
	v_sqrt_f32_e32 v36, v36
	s_nop 0
	v_mul_f32_e32 v2, v2, v36
	ds_write_b32 v111, v1 offset:27840
	ds_write_b32 v111, v2 offset:44480
	v_add_f32_e32 v1, v103, v43
	v_mul_f32_e32 v1, 0xbfb8aa3b, v1
	v_exp_f32_e32 v1, v1
	ds_read_u16 v3, v137
	v_add_f32_e32 v1, 1.0, v1
	v_rcp_f32_e32 v2, v1
	v_add_f32_e32 v1, v104, v39
	v_mul_f32_e32 v1, 0xbfb8aa3b, v1
	v_exp_f32_e32 v1, v1
	v_mul_f32_e32 v2, v108, v2
	v_mul_f32_e32 v2, 0x3fb8aa3b, v2
	v_exp_f32_e32 v2, v2
	v_add_f32_e32 v1, 1.0, v1
	v_rcp_f32_e32 v1, v1
	s_waitcnt lgkmcnt(0)
	v_lshlrev_b32_e32 v3, 16, v3
	v_fma_f32 v36, -v2, v2, 1.0
	v_max_f32_e32 v36, 0, v36
	v_sqrt_f32_e32 v36, v36
	v_mul_f32_e32 v1, v1, v3
	v_mul_f32_e32 v1, v36, v1
	ds_write_b32 v114, v2 offset:27840
	ds_write_b32 v114, v1 offset:44480
	s_waitcnt vmcnt(0) lgkmcnt(0)
	s_barrier
	s_cmp_lt_u32 s20, 8
	s_cbranch_scc1 .Lfg_nold_s
	s_sub_i32 s38, 15, s20
	s_and_b64 s[18:19], s[12:13], exec
	s_cselect_b32 s38, s20, s38
	s_mov_b32 s39, 0xfe000000
	s_cselect_b32 s39, 0x2000000, s39
	s_mov_b32 s41, 0x2000000
	s_cselect_b32 s41, 0x4000000, s41
	s_lshl_b32 s38, s38, 6
	s_add_i32 s38, s38, s34
	v_or_b32_e32 v202, s38, v93
	v_lshl_add_u32 v228, v202, 11, s39
	v_ashrrev_i32_e32 v229, 31, v228
	v_lshl_add_u64 v[228:229], v[78:79], 0, v[228:229]
	v_lshl_add_u32 v238, v202, 12, s41
	v_mov_b32_e32 v239, 0
	v_lshl_add_u64 v[238:239], v[78:79], 0, v[238:239]
	global_load_dwordx4 v[228:231], v[228:229], off
	global_load_dwordx4 v[238:241], v[238:239], off
	v_or_b32_e32 v202, s38, v95
	v_lshl_add_u32 v250, v202, 11, s39
	v_ashrrev_i32_e32 v251, 31, v250
	v_lshl_add_u64 v[250:251], v[78:79], 0, v[250:251]
	v_lshl_add_u32 v202, v202, 12, s41
	v_mov_b32_e32 v203, 0
	v_lshl_add_u64 v[202:203], v[78:79], 0, v[202:203]
	global_load_dwordx4 v[250:253], v[250:251], off
	global_load_dword v69, v[202:203], off
	global_load_dword v90, v[202:203], off offset:4
	global_load_dword v189, v[202:203], off offset:8
	global_load_dword v207, v[202:203], off offset:12
.Lfg_nold_s:
	s_and_b64 s[18:19], s[12:13], exec
	s_cselect_b32 s21, 0, 0x3ffc
	s_cselect_b32 s16, 1, -1
	s_mulk_i32 s16, 0x104
	v_readfirstlane_b32 s32, v92
	s_lshr_b32 s32, s32, 6
	s_and_b32 s32, s32, 3
	v_and_b32_e32 v147, 63, v92
	v_lshl_add_u32 v176, v147, 3, s40
	v_lshl_add_u32 v147, v147, 2, s40
	s_mul_i32 s17, s16, s32
	s_lshl_b32 s17, s17, 4
	s_add_i32 s17, s17, s21
	v_add_u32_e32 v1, s17, v147
	v_add_u32_e32 v2, s16, v1
	v_add_u32_e32 v3, s16, v2
	v_add_u32_e32 v36, s16, v3
	v_add_u32_e32 v37, s16, v36
	v_add_u32_e32 v38, s16, v37
	v_add_u32_e32 v39, s16, v38
	v_add_u32_e32 v40, s16, v39
	v_add_u32_e32 v41, s16, v40
	v_add_u32_e32 v42, s16, v41
	v_add_u32_e32 v43, s16, v42
	v_add_u32_e32 v64, s16, v43
	v_add_u32_e32 v65, s16, v64
	v_add_u32_e32 v66, s16, v65
	v_add_u32_e32 v67, s16, v66
	v_add_u32_e32 v68, s16, v67
	ds_read2st64_b32 v[148:149], v1 offset0:108 offset1:173
	ds_read2st64_b32 v[150:151], v2 offset0:108 offset1:173
	ds_read2st64_b32 v[152:153], v3 offset0:108 offset1:173
	ds_read2st64_b32 v[154:155], v36 offset0:108 offset1:173
	ds_read2st64_b32 v[156:157], v37 offset0:108 offset1:173
	ds_read2st64_b32 v[158:159], v38 offset0:108 offset1:173
	ds_read2st64_b32 v[160:161], v39 offset0:108 offset1:173
	ds_read2st64_b32 v[162:163], v40 offset0:108 offset1:173
	ds_read2st64_b32 v[164:165], v41 offset0:108 offset1:173
	ds_read2st64_b32 v[166:167], v42 offset0:108 offset1:173
	ds_read2st64_b32 v[168:169], v43 offset0:108 offset1:173
	ds_read2st64_b32 v[170:171], v64 offset0:108 offset1:173
	ds_read2st64_b32 v[242:243], v65 offset0:108 offset1:173
	ds_read2st64_b32 v[244:245], v66 offset0:108 offset1:173
	ds_read2st64_b32 v[246:247], v67 offset0:108 offset1:173
	ds_read2st64_b32 v[248:249], v68 offset0:108 offset1:173
	s_lshl_b32 s15, s32, 9
	v_add_u32_e32 v139, s15, v176
	s_waitcnt lgkmcnt(14)
	v_fmac_f32_e32 v151, v150, v149
	v_mul_f32_e32 v150, v150, v148
	s_waitcnt lgkmcnt(13)
	v_fmac_f32_e32 v153, v152, v151
	v_mul_f32_e32 v152, v152, v150
	s_waitcnt lgkmcnt(12)
	v_fmac_f32_e32 v155, v154, v153
	v_mul_f32_e32 v154, v154, v152
	s_waitcnt lgkmcnt(11)
	v_fmac_f32_e32 v157, v156, v155
	v_mul_f32_e32 v156, v156, v154
	s_waitcnt lgkmcnt(10)
	v_fmac_f32_e32 v159, v158, v157
	v_mul_f32_e32 v158, v158, v156
	s_waitcnt lgkmcnt(9)
	v_fmac_f32_e32 v161, v160, v159
	v_mul_f32_e32 v160, v160, v158
	s_waitcnt lgkmcnt(8)
	v_fmac_f32_e32 v163, v162, v161
	v_mul_f32_e32 v162, v162, v160
	s_waitcnt lgkmcnt(7)
	v_fmac_f32_e32 v165, v164, v163
	v_mul_f32_e32 v164, v164, v162
	s_waitcnt lgkmcnt(6)
	v_fmac_f32_e32 v167, v166, v165
	v_mul_f32_e32 v166, v166, v164
	s_waitcnt lgkmcnt(5)
	v_fmac_f32_e32 v169, v168, v167
	v_mul_f32_e32 v168, v168, v166
	s_waitcnt lgkmcnt(4)
	v_fmac_f32_e32 v171, v170, v169
	v_mul_f32_e32 v170, v170, v168
	s_waitcnt lgkmcnt(3)
	v_fmac_f32_e32 v243, v242, v171
	v_mul_f32_e32 v242, v242, v170
	s_waitcnt lgkmcnt(2)
	v_fmac_f32_e32 v245, v244, v243
	v_mul_f32_e32 v244, v244, v242
	s_waitcnt lgkmcnt(1)
	v_fmac_f32_e32 v247, v246, v245
	v_mul_f32_e32 v246, v246, v244
	s_waitcnt lgkmcnt(0)
	v_fmac_f32_e32 v249, v248, v247
	v_mul_f32_e32 v248, v248, v246
	ds_write_b64 v139, v[248:249] offset:61440
	s_cmp_lg_u32 s20, 0
	s_cbranch_scc1 .Lps_skipcw_s
	s_cmp_lg_u32 s32, 0
	s_cbranch_scc1 .Lps_skipcw_s
	ds_write_b32 v147, v91 offset:63488

.LBB0_361:
	s_or_b64 exec, exec, s[4:5]
	s_mov_b64 s[6:7], s[26:27]
	s_mov_b64 s[8:9], s[26:27]
	s_mov_b64 s[10:11], s[26:27]
	s_mov_b64 s[12:13], s[26:27]
	s_waitcnt lgkmcnt(0)
	v_mov_b32_e32 v2, v179
	v_readlane_b32 s4, v254, 5
	s_barrier
	s_nop 0
	v_add_u32_e32 v1, s4, v2
	v_cmp_gt_i32_e32 vcc, s49, v1
	s_and_saveexec_b64 s[4:5], vcc
	s_cbranch_execz .LBB0_364
	s_add_u32 s6, s6, 0x7100000
	s_addc_u32 s7, s7, 0
	s_add_u32 s8, s8, 0x9100000
	s_addc_u32 s9, s9, 0
	s_add_u32 s10, s10, 0xb100000
	s_addc_u32 s11, s11, 0
	s_add_u32 s12, s12, 0x16100000
	s_addc_u32 s13, s13, 0
	v_readlane_b32 s17, v254, 2
	s_nop 0
	s_cmpk_lt_i32 s17, 0x100
	s_cbranch_scc0 .LBB0_364
.LBB0_364:
	s_or_b64 exec, exec, s[4:5]
	s_mov_b64 s[6:7], s[26:27]
	s_getreg_b32 s8, hwreg(HW_REG_XCC_ID, 0, 4)
	s_waitcnt vmcnt(0)
	s_barrier
	s_mov_b64 s[4:5], exec
	v_readlane_b32 s10, v254, 0
	v_readlane_b32 s11, v254, 1
	s_and_b64 s[10:11], s[4:5], s[10:11]
	s_mov_b64 exec, s[10:11]
	s_cbranch_execz .LBB0_417
	v_readlane_b32 s9, v254, 36
	s_waitcnt vmcnt(0) expcnt(0) lgkmcnt(0)
	s_and_b32 s18, s8, 15
	v_mov_b32_e32 v1, s9
	ds_read_b32 v3, v1
	v_readlane_b32 s9, v254, 37
	s_waitcnt lgkmcnt(0)
	v_cmp_ne_u32_e32 vcc, 0, v3
	v_mov_b32_e32 v1, s9
	ds_read_b32 v2, v1
	s_cbranch_vccnz .LBB0_381
	s_add_u32 s8, s6, 0x10200
	s_addc_u32 s9, s7, 0
	s_add_u32 s10, s6, 0x10400
	s_addc_u32 s11, s7, 0
	s_add_u32 s12, s6, 0x10500
	s_addc_u32 s13, s7, 0
	s_add_u32 s14, s6, 0x10600
	s_addc_u32 s15, s7, 0
	s_add_u32 s16, s6, 0x10700
	s_addc_u32 s17, s7, 0
	s_add_u32 s20, s6, 0x10800
	s_addc_u32 s21, s7, 0
	s_add_u32 s22, s6, 0x10900
	s_addc_u32 s23, s7, 0
	s_add_u32 s28, s6, 0x10a00
	s_addc_u32 s29, s7, 0
	s_add_u32 s34, s6, 0x10b00
	s_addc_u32 s35, s7, 0
	s_add_u32 s38, s6, 0x10c00
	s_addc_u32 s39, s7, 0
	s_add_u32 s40, s6, 0x10d00
	s_addc_u32 s41, s7, 0
	s_add_u32 s42, s6, 0x10e00
	s_addc_u32 s43, s7, 0
	s_add_u32 s48, s6, 0x10f00
	s_addc_u32 s49, s7, 0
	s_add_u32 s50, s6, 0x11000
	s_addc_u32 s51, s7, 0
	s_add_u32 s52, s6, 0x11100
	s_addc_u32 s53, s7, 0
	s_add_u32 s56, s6, 0x11200
	s_addc_u32 s57, s7, 0
	s_add_u32 s58, s6, 0x11300
	s_addc_u32 s59, s7, 0
	s_mov_b32 s19, 1
	s_branch .LBB0_369
